# K-loops: setprio flips removed + one static s_setprio 1 for waves 0-3 before each K-loop
# speedup vs baseline: 1.0006x; 1.0006x over previous
.LBB0_164:
	s_ashr_i32 s61, s60, 31
	s_lshl_b64 s[12:13], s[60:61], 20
	s_add_u32 s64, s24, s12
	s_addc_u32 s65, s25, s13
	s_and_b64 s[12:13], s[6:7], exec
	s_cselect_b32 s9, s65, s21
	s_cselect_b32 s61, s64, s20
	s_ashr_i32 s63, s62, 31
	s_lshl_b64 s[12:13], s[62:63], 20
	s_add_u32 s66, s42, s12
	s_addc_u32 s67, s43, s13
	s_and_b64 s[12:13], s[6:7], exec
	s_cselect_b32 s63, s67, s1
	s_cselect_b32 s75, s66, s0
	s_add_u32 s70, s20, 0x80080
	s_addc_u32 s71, s21, 0
	s_add_u32 s20, s0, 0x100
	v_mov_b32_e32 v2, 0
	s_addc_u32 s21, s1, 0
	s_mov_b32 s76, -2
	v_mov_b32_e32 v3, v2
	v_mov_b32_e32 v4, v2
	v_mov_b32_e32 v5, v2
	v_mov_b32_e32 v6, v2
	v_mov_b32_e32 v7, v2
	v_mov_b32_e32 v8, v2
	v_mov_b32_e32 v9, v2
	v_mov_b32_e32 v18, v2
	v_mov_b32_e32 v19, v2
	v_mov_b32_e32 v20, v2
	v_mov_b32_e32 v21, v2
	v_mov_b32_e32 v22, v2
	v_mov_b32_e32 v23, v2
	v_mov_b32_e32 v24, v2
	v_mov_b32_e32 v25, v2
	v_mov_b32_e32 v34, v2
	v_mov_b32_e32 v35, v2
	v_mov_b32_e32 v36, v2
	v_mov_b32_e32 v37, v2
	v_mov_b32_e32 v38, v2
	v_mov_b32_e32 v39, v2
	v_mov_b32_e32 v40, v2
	v_mov_b32_e32 v41, v2
	v_mov_b32_e32 v50, v2
	v_mov_b32_e32 v51, v2
	v_mov_b32_e32 v52, v2
	v_mov_b32_e32 v53, v2
	v_mov_b32_e32 v54, v2
	v_mov_b32_e32 v55, v2
	v_mov_b32_e32 v56, v2
	v_mov_b32_e32 v57, v2
	v_mov_b32_e32 v10, v2
	v_mov_b32_e32 v11, v2
	v_mov_b32_e32 v12, v2
	v_mov_b32_e32 v13, v2
	v_mov_b32_e32 v14, v2
	v_mov_b32_e32 v15, v2
	v_mov_b32_e32 v16, v2
	v_mov_b32_e32 v17, v2
	v_mov_b32_e32 v26, v2
	v_mov_b32_e32 v27, v2
	v_mov_b32_e32 v28, v2
	v_mov_b32_e32 v29, v2
	v_mov_b32_e32 v30, v2
	v_mov_b32_e32 v31, v2
	v_mov_b32_e32 v32, v2
	v_mov_b32_e32 v33, v2
	v_mov_b32_e32 v42, v2
	v_mov_b32_e32 v43, v2
	v_mov_b32_e32 v44, v2
	v_mov_b32_e32 v45, v2
	v_mov_b32_e32 v46, v2
	v_mov_b32_e32 v47, v2
	v_mov_b32_e32 v48, v2
	v_mov_b32_e32 v49, v2
	v_mov_b32_e32 v58, v2
	v_mov_b32_e32 v59, v2
	v_mov_b32_e32 v60, v2
	v_mov_b32_e32 v61, v2
	v_mov_b32_e32 v62, v2
	v_mov_b32_e32 v63, v2
	v_mov_b32_e32 v64, v2
	v_mov_b32_e32 v65, v2
	v_mov_b32_e32 v66, v2
	v_mov_b32_e32 v67, v2
	v_mov_b32_e32 v68, v2
	v_mov_b32_e32 v69, v2
	v_mov_b32_e32 v70, v2
	v_mov_b32_e32 v71, v2
	v_mov_b32_e32 v72, v2
	v_mov_b32_e32 v73, v2
	v_mov_b32_e32 v82, v2
	v_mov_b32_e32 v83, v2
	v_mov_b32_e32 v84, v2
	v_mov_b32_e32 v85, v2
	v_mov_b32_e32 v86, v2
	v_mov_b32_e32 v87, v2
	v_mov_b32_e32 v88, v2
	v_mov_b32_e32 v89, v2
	v_mov_b32_e32 v98, v2
	v_mov_b32_e32 v99, v2
	v_mov_b32_e32 v100, v2
	v_mov_b32_e32 v101, v2
	v_mov_b32_e32 v102, v2
	v_mov_b32_e32 v103, v2
	v_mov_b32_e32 v104, v2
	v_mov_b32_e32 v105, v2
	v_mov_b32_e32 v130, v2
	v_mov_b32_e32 v131, v2
	v_mov_b32_e32 v132, v2
	v_mov_b32_e32 v133, v2
	v_mov_b32_e32 v134, v2
	v_mov_b32_e32 v135, v2
	v_mov_b32_e32 v136, v2
	v_mov_b32_e32 v137, v2
	v_mov_b32_e32 v74, v2
	v_mov_b32_e32 v75, v2
	v_mov_b32_e32 v76, v2
	v_mov_b32_e32 v77, v2
	v_mov_b32_e32 v78, v2
	v_mov_b32_e32 v79, v2
	v_mov_b32_e32 v80, v2
	v_mov_b32_e32 v81, v2
	v_mov_b32_e32 v90, v2
	v_mov_b32_e32 v91, v2
	v_mov_b32_e32 v92, v2
	v_mov_b32_e32 v93, v2
	v_mov_b32_e32 v94, v2
	v_mov_b32_e32 v95, v2
	v_mov_b32_e32 v96, v2
	v_mov_b32_e32 v97, v2
	v_mov_b32_e32 v106, v2
	v_mov_b32_e32 v107, v2
	v_mov_b32_e32 v108, v2
	v_mov_b32_e32 v109, v2
	v_mov_b32_e32 v110, v2
	v_mov_b32_e32 v111, v2
	v_mov_b32_e32 v112, v2
	v_mov_b32_e32 v113, v2
	v_mov_b32_e32 v138, v2
	v_mov_b32_e32 v139, v2
	v_mov_b32_e32 v140, v2
	v_mov_b32_e32 v141, v2
	v_mov_b32_e32 v142, v2
	v_mov_b32_e32 v143, v2
	v_mov_b32_e32 v144, v2
	v_mov_b32_e32 v145, v2
	s_cmp_eq_u64 s[56:57], 0
	s_cbranch_scc1 .Lprio_p1
	s_setprio 1

.LBB0_496:
	s_mov_b32 s47, s61
	s_mov_b32 s62, s61
	s_add_i32 s61, s46, s10
	s_mov_b64 s[8:9], s[14:15]
	s_and_b64 s[14:15], s[44:45], exec
	s_cselect_b32 s14, s61, s47
	s_ashr_i32 s15, s14, 31
	s_lshl_b64 s[14:15], s[14:15], 20
	s_add_u32 s14, s18, s14
	s_addc_u32 s15, s19, s15
	s_and_b64 s[46:47], s[44:45], exec
	s_cselect_b32 s63, s15, s9
	s_cselect_b32 s64, s14, s8
	s_add_u32 s8, s8, 0x80080
	v_mov_b32_e32 v60, 0
	s_addc_u32 s9, s9, 0
	s_mov_b32 s65, -2
	s_mov_b64 s[46:47], s[26:27]
	v_mov_b32_e32 v61, v60
	v_mov_b32_e32 v62, v60
	v_mov_b32_e32 v63, v60
	v_mov_b32_e32 v56, v60
	v_mov_b32_e32 v57, v60
	v_mov_b32_e32 v58, v60
	v_mov_b32_e32 v59, v60
	v_mov_b32_e32 v36, v60
	v_mov_b32_e32 v37, v60
	v_mov_b32_e32 v38, v60
	v_mov_b32_e32 v39, v60
	v_mov_b32_e32 v32, v60
	v_mov_b32_e32 v33, v60
	v_mov_b32_e32 v34, v60
	v_mov_b32_e32 v35, v60
	v_mov_b32_e32 v16, v60
	v_mov_b32_e32 v17, v60
	v_mov_b32_e32 v18, v60
	v_mov_b32_e32 v19, v60
	v_mov_b32_e32 v8, v60
	v_mov_b32_e32 v9, v60
	v_mov_b32_e32 v10, v60
	v_mov_b32_e32 v11, v60
	v_mov_b32_e32 v4, v60
	v_mov_b32_e32 v5, v60
	v_mov_b32_e32 v6, v60
	v_mov_b32_e32 v7, v60
	v_mov_b32_e32 v0, v60
	v_mov_b32_e32 v1, v60
	v_mov_b32_e32 v2, v60
	v_mov_b32_e32 v3, v60
	v_mov_b32_e32 v52, v60
	v_mov_b32_e32 v53, v60
	v_mov_b32_e32 v54, v60
	v_mov_b32_e32 v55, v60
	v_mov_b32_e32 v48, v60
	v_mov_b32_e32 v49, v60
	v_mov_b32_e32 v50, v60
	v_mov_b32_e32 v51, v60
	v_mov_b32_e32 v44, v60
	v_mov_b32_e32 v45, v60
	v_mov_b32_e32 v46, v60
	v_mov_b32_e32 v47, v60
	v_mov_b32_e32 v40, v60
	v_mov_b32_e32 v41, v60
	v_mov_b32_e32 v42, v60
	v_mov_b32_e32 v43, v60
	v_mov_b32_e32 v28, v60
	v_mov_b32_e32 v29, v60
	v_mov_b32_e32 v30, v60
	v_mov_b32_e32 v31, v60
	v_mov_b32_e32 v24, v60
	v_mov_b32_e32 v25, v60
	v_mov_b32_e32 v26, v60
	v_mov_b32_e32 v27, v60
	v_mov_b32_e32 v20, v60
	v_mov_b32_e32 v21, v60
	v_mov_b32_e32 v22, v60
	v_mov_b32_e32 v23, v60
	v_mov_b32_e32 v12, v60
	v_mov_b32_e32 v13, v60
	v_mov_b32_e32 v14, v60
	v_mov_b32_e32 v15, v60
	v_mov_b32_e32 v88, v60
	v_mov_b32_e32 v89, v60
	v_mov_b32_e32 v90, v60
	v_mov_b32_e32 v91, v60
	v_mov_b32_e32 v80, v60
	v_mov_b32_e32 v81, v60
	v_mov_b32_e32 v82, v60
	v_mov_b32_e32 v83, v60
	v_mov_b32_e32 v104, v60
	v_mov_b32_e32 v105, v60
	v_mov_b32_e32 v106, v60
	v_mov_b32_e32 v107, v60
	v_mov_b32_e32 v84, v60
	v_mov_b32_e32 v85, v60
	v_mov_b32_e32 v86, v60
	v_mov_b32_e32 v87, v60
	v_mov_b32_e32 v68, v60
	v_mov_b32_e32 v69, v60
	v_mov_b32_e32 v70, v60
	v_mov_b32_e32 v71, v60
	v_mov_b32_e32 v64, v60
	v_mov_b32_e32 v65, v60
	v_mov_b32_e32 v66, v60
	v_mov_b32_e32 v67, v60
	v_mov_b32_e32 v72, v60
	v_mov_b32_e32 v73, v60
	v_mov_b32_e32 v74, v60
	v_mov_b32_e32 v75, v60
	v_mov_b32_e32 v92, v60
	v_mov_b32_e32 v93, v60
	v_mov_b32_e32 v94, v60
	v_mov_b32_e32 v95, v60
	v_mov_b32_e32 v116, v60
	v_mov_b32_e32 v117, v60
	v_mov_b32_e32 v118, v60
	v_mov_b32_e32 v119, v60
	v_mov_b32_e32 v112, v60
	v_mov_b32_e32 v113, v60
	v_mov_b32_e32 v114, v60
	v_mov_b32_e32 v115, v60
	v_mov_b32_e32 v120, v60
	v_mov_b32_e32 v121, v60
	v_mov_b32_e32 v122, v60
	v_mov_b32_e32 v123, v60
	v_mov_b32_e32 v124, v60
	v_mov_b32_e32 v125, v60
	v_mov_b32_e32 v126, v60
	v_mov_b32_e32 v127, v60
	v_mov_b32_e32 v76, v60
	v_mov_b32_e32 v77, v60
	v_mov_b32_e32 v78, v60
	v_mov_b32_e32 v79, v60
	v_mov_b32_e32 v128, v60
	v_mov_b32_e32 v129, v60
	v_mov_b32_e32 v130, v60
	v_mov_b32_e32 v131, v60
	v_mov_b32_e32 v96, v60
	v_mov_b32_e32 v97, v60
	v_mov_b32_e32 v98, v60
	v_mov_b32_e32 v99, v60
	v_mov_b32_e32 v100, v60
	v_mov_b32_e32 v101, v60
	v_mov_b32_e32 v102, v60
	v_mov_b32_e32 v103, v60
	s_cmp_eq_u64 s[36:37], 0
	s_cbranch_scc1 .Lprio_p4
	s_setprio 1
